# v29 + priority 2 (instead of 0) while a wave issues its second fragment-read group between the two MFMA bursts of a K-step
# baseline (speedup 1.0000x reference)
.LBB0_303:
	s_setprio 3
	s_and_b32 s1, s0, 0x2000
	s_xor_b32 s8, s1, 0x2000
	s_lshl_b32 s101, s8, 1
	s_add_u32 s101, s101, s100
	s_add_u32 m0, s101, 0x0
	s_nop 0
	global_load_lds_dwordx4 v[184:185], off
	s_add_u32 m0, s101, 0x1000
	v_lshl_add_u64 v[184:185], v[184:185], 0, vcc
	global_load_lds_dwordx4 v[186:187], off
	s_add_u32 m0, s101, 0x2000
	v_lshl_add_u64 v[186:187], v[186:187], 0, vcc
	global_load_lds_dwordx4 v[188:189], off
	s_add_u32 m0, s101, 0x3000
	v_lshl_add_u64 v[188:189], v[188:189], 0, vcc
	global_load_lds_dwordx4 v[190:191], off
	s_add_u32 m0, s101, 0x8000
	v_lshl_add_u64 v[190:191], v[190:191], 0, vcc
	global_load_lds_dwordx4 v[192:193], off
	s_add_u32 m0, s101, 0x9000
	v_lshl_add_u64 v[192:193], v[192:193], 0, vcc
	global_load_lds_dwordx4 v[194:195], off
	s_add_u32 m0, s101, 0xa000
	v_lshl_add_u64 v[194:195], v[194:195], 0, vcc
	global_load_lds_dwordx4 v[196:197], off
	s_add_u32 m0, s101, 0xb000
	v_lshl_add_u64 v[196:197], v[196:197], 0, vcc
	global_load_lds_dwordx4 v[198:199], off
	v_lshl_add_u64 v[198:199], v[198:199], 0, vcc
	s_lshl_b32 s1, s1, 1
	v_add_u32_e32 v82, s1, v86
	v_add_u32_e32 v83, s1, v85
	v_add_u32_e32 v95, v82, v93
	ds_read_b128 v[96:99], v95
	ds_read_b128 v[100:103], v95 offset:2048
	ds_read_b128 v[120:123], v95 offset:4096
	ds_read_b128 v[124:127], v95 offset:6144
	v_add_u32_e32 v95, v83, v93
	ds_read_b128 v[128:131], v95 offset:32768
	ds_read_b128 v[132:135], v95 offset:34816
	ds_read_b128 v[136:139], v95 offset:36864
	ds_read_b128 v[140:143], v95 offset:38912
	s_setprio 1
	s_waitcnt lgkmcnt(0)
	v_mfma_f32_16x16x32_bf16 v[60:63], v[128:131], v[96:99], v[60:63]
	v_mfma_f32_16x16x32_bf16 v[56:59], v[132:135], v[96:99], v[56:59]
	v_mfma_f32_16x16x32_bf16 v[52:55], v[136:139], v[96:99], v[52:55]
	v_mfma_f32_16x16x32_bf16 v[48:51], v[140:143], v[96:99], v[48:51]
	v_mfma_f32_16x16x32_bf16 v[44:47], v[128:131], v[100:103], v[44:47]
	v_mfma_f32_16x16x32_bf16 v[40:43], v[132:135], v[100:103], v[40:43]
	v_mfma_f32_16x16x32_bf16 v[36:39], v[136:139], v[100:103], v[36:39]
	v_mfma_f32_16x16x32_bf16 v[32:35], v[140:143], v[100:103], v[32:35]
	v_mfma_f32_16x16x32_bf16 v[28:31], v[128:131], v[120:123], v[28:31]
	v_mfma_f32_16x16x32_bf16 v[24:27], v[132:135], v[120:123], v[24:27]
	v_mfma_f32_16x16x32_bf16 v[20:23], v[136:139], v[120:123], v[20:23]
	v_mfma_f32_16x16x32_bf16 v[16:19], v[140:143], v[120:123], v[16:19]
	v_mfma_f32_16x16x32_bf16 v[12:15], v[128:131], v[124:127], v[12:15]
	v_mfma_f32_16x16x32_bf16 v[8:11], v[132:135], v[124:127], v[8:11]
	v_mfma_f32_16x16x32_bf16 v[4:7], v[136:139], v[124:127], v[4:7]
	v_mfma_f32_16x16x32_bf16 v[0:3], v[140:143], v[124:127], v[0:3]
	s_setprio 2
	v_add_u32_e32 v82, v82, v94
	ds_read_b128 v[96:99], v82
	ds_read_b128 v[100:103], v82 offset:2048
	ds_read_b128 v[120:123], v82 offset:4096
	ds_read_b128 v[124:127], v82 offset:6144
	v_add_u32_e32 v82, v83, v94
	ds_read_b128 v[128:131], v82 offset:32768
	ds_read_b128 v[132:135], v82 offset:34816
	ds_read_b128 v[136:139], v82 offset:36864
	ds_read_b128 v[140:143], v82 offset:38912
	s_setprio 1
	s_waitcnt lgkmcnt(0)
	v_mfma_f32_16x16x32_bf16 v[60:63], v[128:131], v[96:99], v[60:63]
	v_mfma_f32_16x16x32_bf16 v[56:59], v[132:135], v[96:99], v[56:59]
	v_mfma_f32_16x16x32_bf16 v[52:55], v[136:139], v[96:99], v[52:55]
	v_mfma_f32_16x16x32_bf16 v[48:51], v[140:143], v[96:99], v[48:51]
	v_mfma_f32_16x16x32_bf16 v[44:47], v[128:131], v[100:103], v[44:47]
	v_mfma_f32_16x16x32_bf16 v[40:43], v[132:135], v[100:103], v[40:43]
	v_mfma_f32_16x16x32_bf16 v[36:39], v[136:139], v[100:103], v[36:39]
	v_mfma_f32_16x16x32_bf16 v[32:35], v[140:143], v[100:103], v[32:35]
	v_mfma_f32_16x16x32_bf16 v[28:31], v[128:131], v[120:123], v[28:31]
	v_mfma_f32_16x16x32_bf16 v[24:27], v[132:135], v[120:123], v[24:27]
	v_mfma_f32_16x16x32_bf16 v[20:23], v[136:139], v[120:123], v[20:23]
	v_mfma_f32_16x16x32_bf16 v[16:19], v[140:143], v[120:123], v[16:19]
	v_mfma_f32_16x16x32_bf16 v[12:15], v[128:131], v[124:127], v[12:15]
	v_mfma_f32_16x16x32_bf16 v[8:11], v[132:135], v[124:127], v[8:11]
	v_mfma_f32_16x16x32_bf16 v[4:7], v[136:139], v[124:127], v[4:7]
	v_mfma_f32_16x16x32_bf16 v[0:3], v[140:143], v[124:127], v[0:3]
	s_setprio 0
	s_addk_i32 s0, 0x2000
	s_waitcnt vmcnt(0)
	s_add_u32 s20, s20, 0x80
	s_addc_u32 s21, s21, 0
	s_cmpk_lg_i32 s20, 0x780
	s_waitcnt vmcnt(0)
	s_barrier
	s_cbranch_scc1 .LBB0_303
	ds_read_b128 v[78:81], v89 offset:55296
	ds_read_b128 v[96:99], v89 offset:53248
	ds_read_b128 v[100:103], v89 offset:51200
	ds_read_b128 v[120:123], v89 offset:49152
	ds_read_b128 v[124:127], v90 offset:22528
	ds_read_b128 v[128:131], v90 offset:20480
	ds_read_b128 v[132:135], v90 offset:18432
	ds_read_b128 v[136:139], v90 offset:16384
	s_setprio 1
	s_waitcnt lgkmcnt(0)
	v_mfma_f32_16x16x32_bf16 v[60:63], v[120:123], v[136:139], v[60:63]
	v_mfma_f32_16x16x32_bf16 v[56:59], v[100:103], v[136:139], v[56:59]
	v_mfma_f32_16x16x32_bf16 v[52:55], v[96:99], v[136:139], v[52:55]
	v_mfma_f32_16x16x32_bf16 v[48:51], v[78:81], v[136:139], v[48:51]
	v_mfma_f32_16x16x32_bf16 v[44:47], v[120:123], v[132:135], v[44:47]
	v_mfma_f32_16x16x32_bf16 v[40:43], v[100:103], v[132:135], v[40:43]
	v_mfma_f32_16x16x32_bf16 v[36:39], v[96:99], v[132:135], v[36:39]
	v_mfma_f32_16x16x32_bf16 v[32:35], v[78:81], v[132:135], v[32:35]
	v_mfma_f32_16x16x32_bf16 v[28:31], v[120:123], v[128:131], v[28:31]
	v_mfma_f32_16x16x32_bf16 v[24:27], v[100:103], v[128:131], v[24:27]
	v_mfma_f32_16x16x32_bf16 v[20:23], v[96:99], v[128:131], v[20:23]
	v_mfma_f32_16x16x32_bf16 v[16:19], v[78:81], v[128:131], v[16:19]
	v_mfma_f32_16x16x32_bf16 v[12:15], v[120:123], v[124:127], v[12:15]
	v_mfma_f32_16x16x32_bf16 v[8:11], v[100:103], v[124:127], v[8:11]
	v_mfma_f32_16x16x32_bf16 v[4:7], v[96:99], v[124:127], v[4:7]
	v_mfma_f32_16x16x32_bf16 v[0:3], v[78:81], v[124:127], v[0:3]
	s_setprio 0
	ds_read_b128 v[78:81], v91 offset:16384
	ds_read_b128 v[96:99], v91 offset:18432
	ds_read_b128 v[100:103], v91 offset:20480
	ds_read_b128 v[120:123], v91 offset:22528
	ds_read_b128 v[124:127], v92 offset:49152
	ds_read_b128 v[128:131], v92 offset:51200
	ds_read_b128 v[132:135], v92 offset:53248
	ds_read_b128 v[136:139], v92 offset:55296
	s_setprio 1
	s_waitcnt lgkmcnt(3)
	v_mfma_f32_16x16x32_bf16 v[60:63], v[124:127], v[78:81], v[60:63]
	s_waitcnt lgkmcnt(2)
	v_mfma_f32_16x16x32_bf16 v[56:59], v[128:131], v[78:81], v[56:59]
	s_waitcnt lgkmcnt(1)
	v_mfma_f32_16x16x32_bf16 v[52:55], v[132:135], v[78:81], v[52:55]
	s_waitcnt lgkmcnt(0)
	v_mfma_f32_16x16x32_bf16 v[48:51], v[136:139], v[78:81], v[48:51]
	v_mfma_f32_16x16x32_bf16 v[44:47], v[124:127], v[96:99], v[44:47]
	v_mfma_f32_16x16x32_bf16 v[40:43], v[128:131], v[96:99], v[40:43]
	v_mfma_f32_16x16x32_bf16 v[36:39], v[132:135], v[96:99], v[36:39]
	v_mfma_f32_16x16x32_bf16 v[32:35], v[136:139], v[96:99], v[32:35]
	v_mfma_f32_16x16x32_bf16 v[28:31], v[124:127], v[100:103], v[28:31]
	v_mfma_f32_16x16x32_bf16 v[24:27], v[128:131], v[100:103], v[24:27]
	v_mfma_f32_16x16x32_bf16 v[20:23], v[132:135], v[100:103], v[20:23]
	v_mfma_f32_16x16x32_bf16 v[16:19], v[136:139], v[100:103], v[16:19]
	v_mfma_f32_16x16x32_bf16 v[12:15], v[124:127], v[120:123], v[12:15]
	v_mfma_f32_16x16x32_bf16 v[8:11], v[128:131], v[120:123], v[8:11]
	v_mfma_f32_16x16x32_bf16 v[4:7], v[132:135], v[120:123], v[4:7]
	v_mfma_f32_16x16x32_bf16 v[0:3], v[136:139], v[120:123], v[0:3]
	s_setprio 0
	s_waitcnt vmcnt(0)
	s_cmp_lt_i32 s10, 32
	s_mov_b64 s[0:1], -1
	s_barrier
	s_cbranch_scc1 .LBB0_594
	s_cmp_eq_u32 s10, 32
	s_cselect_b64 s[0:1], -1, 0
	s_and_b64 vcc, exec, s[0:1]
	v_mov_b32_e32 v79, v63
	v_mov_b32_e32 v82, v62
	v_mov_b32_e32 v83, v61
	v_mov_b32_e32 v95, v60
	s_cbranch_vccz .LBB0_323
	v_cmp_nlt_f32_e64 s[8:9], |v60|, s33
	s_and_saveexec_b64 s[12:13], s[8:9]
	s_xor_b64 s[8:9], exec, s[12:13]
	s_cbranch_execz .LBB0_308
	v_add_f32_e64 v78, |v60|, |v60|
	v_mul_f32_e32 v79, 0x3fb8aa3b, v78
	v_rndne_f32_e32 v80, v79
	s_mov_b32 s11, 0x3fb8aa3b
	v_sub_f32_e32 v81, v79, v80
	v_fma_f32 v79, v78, s11, -v79
	v_fmac_f32_e32 v79, 0x32a5705f, v78
	v_add_f32_e32 v79, v81, v79
	v_cvt_i32_f32_e32 v80, v80
	v_exp_f32_e32 v79, v79
	s_mov_b32 s11, 0xc2ce8ed0
	v_cmp_ngt_f32_e32 vcc, s11, v78
	s_mov_b32 s11, 0x42b17218
	v_ldexp_f32 v79, v79, v80
	v_cndmask_b32_e32 v79, 0, v79, vcc
	v_cmp_nlt_f32_e32 vcc, s11, v78
	s_nop 1
	v_cndmask_b32_e32 v78, v112, v79, vcc
	v_add_f32_e32 v78, 1.0, v78
	v_rcp_f32_e32 v78, v78
	s_nop 0
	v_fma_f32 v78, v78, -2.0, 1.0

.LBB0_882:
	s_setprio 3
	s_and_b32 s6, s0, 0x2000
	s_xor_b32 s8, s6, 0x2000
	s_lshl_b32 s101, s8, 1
	s_add_u32 s101, s101, s100
	s_add_u32 m0, s101, 0x0
	s_nop 0
	global_load_lds_dwordx4 v[184:185], off
	s_add_u32 m0, s101, 0x1000
	v_lshl_add_u64 v[184:185], v[184:185], 0, vcc
	global_load_lds_dwordx4 v[186:187], off
	s_add_u32 m0, s101, 0x2000
	v_lshl_add_u64 v[186:187], v[186:187], 0, vcc
	global_load_lds_dwordx4 v[188:189], off
	s_add_u32 m0, s101, 0x3000
	v_lshl_add_u64 v[188:189], v[188:189], 0, vcc
	global_load_lds_dwordx4 v[190:191], off
	s_add_u32 m0, s101, 0x8000
	v_lshl_add_u64 v[190:191], v[190:191], 0, vcc
	global_load_lds_dwordx4 v[192:193], off
	s_add_u32 m0, s101, 0x9000
	v_lshl_add_u64 v[192:193], v[192:193], 0, vcc
	global_load_lds_dwordx4 v[194:195], off
	s_add_u32 m0, s101, 0xa000
	v_lshl_add_u64 v[194:195], v[194:195], 0, vcc
	global_load_lds_dwordx4 v[196:197], off
	s_add_u32 m0, s101, 0xb000
	v_lshl_add_u64 v[196:197], v[196:197], 0, vcc
	global_load_lds_dwordx4 v[198:199], off
	v_lshl_add_u64 v[198:199], v[198:199], 0, vcc
	s_lshl_b32 s6, s6, 1
	v_add_u32_e32 v102, s6, v90
	v_add_u32_e32 v103, s6, v71
	v_add_u32_e32 v128, v102, v96
	v_add_u32_e32 v144, v103, v96
	ds_read_b128 v[98:101], v128
	ds_read_b128 v[120:123], v128 offset:2048
	ds_read_b128 v[124:127], v128 offset:4096
	ds_read_b128 v[128:131], v128 offset:6144
	ds_read_b128 v[132:135], v144 offset:32768
	ds_read_b128 v[136:139], v144 offset:34816
	ds_read_b128 v[140:143], v144 offset:36864
	ds_read_b128 v[144:147], v144 offset:38912
	s_setprio 1
	s_waitcnt lgkmcnt(0)
	v_mfma_f32_16x16x32_bf16 v[60:63], v[132:135], v[98:101], v[60:63]
	v_mfma_f32_16x16x32_bf16 v[56:59], v[136:139], v[98:101], v[56:59]
	v_mfma_f32_16x16x32_bf16 v[52:55], v[140:143], v[98:101], v[52:55]
	v_mfma_f32_16x16x32_bf16 v[48:51], v[144:147], v[98:101], v[48:51]
	v_mfma_f32_16x16x32_bf16 v[44:47], v[132:135], v[120:123], v[44:47]
	v_mfma_f32_16x16x32_bf16 v[40:43], v[136:139], v[120:123], v[40:43]
	v_mfma_f32_16x16x32_bf16 v[36:39], v[140:143], v[120:123], v[36:39]
	v_mfma_f32_16x16x32_bf16 v[32:35], v[144:147], v[120:123], v[32:35]
	v_mfma_f32_16x16x32_bf16 v[28:31], v[132:135], v[124:127], v[28:31]
	v_mfma_f32_16x16x32_bf16 v[24:27], v[136:139], v[124:127], v[24:27]
	v_mfma_f32_16x16x32_bf16 v[20:23], v[140:143], v[124:127], v[20:23]
	v_mfma_f32_16x16x32_bf16 v[16:19], v[144:147], v[124:127], v[16:19]
	v_mfma_f32_16x16x32_bf16 v[12:15], v[132:135], v[128:131], v[12:15]
	v_mfma_f32_16x16x32_bf16 v[8:11], v[136:139], v[128:131], v[8:11]
	v_mfma_f32_16x16x32_bf16 v[4:7], v[140:143], v[128:131], v[4:7]
	v_mfma_f32_16x16x32_bf16 v[0:3], v[144:147], v[128:131], v[0:3]
	s_setprio 2
	v_add_u32_e32 v102, v102, v97
	ds_read_b128 v[98:101], v102
	ds_read_b128 v[120:123], v102 offset:2048
	ds_read_b128 v[124:127], v102 offset:4096
	ds_read_b128 v[128:131], v102 offset:6144
	v_add_u32_e32 v102, v103, v97
	ds_read_b128 v[132:135], v102 offset:32768
	ds_read_b128 v[136:139], v102 offset:34816
	ds_read_b128 v[140:143], v102 offset:36864
	ds_read_b128 v[144:147], v102 offset:38912
	s_setprio 1
	s_waitcnt lgkmcnt(0)
	v_mfma_f32_16x16x32_bf16 v[60:63], v[132:135], v[98:101], v[60:63]
	v_mfma_f32_16x16x32_bf16 v[56:59], v[136:139], v[98:101], v[56:59]
	v_mfma_f32_16x16x32_bf16 v[52:55], v[140:143], v[98:101], v[52:55]
	v_mfma_f32_16x16x32_bf16 v[48:51], v[144:147], v[98:101], v[48:51]
	v_mfma_f32_16x16x32_bf16 v[44:47], v[132:135], v[120:123], v[44:47]
	v_mfma_f32_16x16x32_bf16 v[40:43], v[136:139], v[120:123], v[40:43]
	v_mfma_f32_16x16x32_bf16 v[36:39], v[140:143], v[120:123], v[36:39]
	v_mfma_f32_16x16x32_bf16 v[32:35], v[144:147], v[120:123], v[32:35]
	v_mfma_f32_16x16x32_bf16 v[28:31], v[132:135], v[124:127], v[28:31]
	v_mfma_f32_16x16x32_bf16 v[24:27], v[136:139], v[124:127], v[24:27]
	v_mfma_f32_16x16x32_bf16 v[20:23], v[140:143], v[124:127], v[20:23]
	v_mfma_f32_16x16x32_bf16 v[16:19], v[144:147], v[124:127], v[16:19]
	v_mfma_f32_16x16x32_bf16 v[12:15], v[132:135], v[128:131], v[12:15]
	v_mfma_f32_16x16x32_bf16 v[8:11], v[136:139], v[128:131], v[8:11]
	v_mfma_f32_16x16x32_bf16 v[4:7], v[140:143], v[128:131], v[4:7]
	v_mfma_f32_16x16x32_bf16 v[0:3], v[144:147], v[128:131], v[0:3]
	s_setprio 0
	s_waitcnt vmcnt(0)
	s_add_u32 s36, s36, 0x80
	s_addc_u32 s37, s37, 0
	s_addk_i32 s0, 0x2000
	s_cmpk_lg_i32 s36, 0x780
	s_waitcnt vmcnt(0)
	s_barrier
	s_cbranch_scc1 .LBB0_882
	ds_read_b128 v[86:89], v92 offset:16384
	ds_read_b128 v[98:101], v92 offset:18432
	ds_read_b128 v[120:123], v92 offset:20480
	ds_read_b128 v[124:127], v92 offset:22528
	ds_read_b128 v[128:131], v93 offset:49152
	ds_read_b128 v[132:135], v93 offset:51200
	ds_read_b128 v[136:139], v93 offset:53248
	ds_read_b128 v[140:143], v93 offset:55296
	s_setprio 1
	s_waitcnt lgkmcnt(3)
	v_mfma_f32_16x16x32_bf16 v[60:63], v[128:131], v[86:89], v[60:63]
	s_waitcnt lgkmcnt(2)
	v_mfma_f32_16x16x32_bf16 v[56:59], v[132:135], v[86:89], v[56:59]
	s_waitcnt lgkmcnt(1)
	v_mfma_f32_16x16x32_bf16 v[52:55], v[136:139], v[86:89], v[52:55]
	s_waitcnt lgkmcnt(0)
	v_mfma_f32_16x16x32_bf16 v[48:51], v[140:143], v[86:89], v[48:51]
	v_mfma_f32_16x16x32_bf16 v[40:43], v[132:135], v[98:101], v[40:43]
	v_mfma_f32_16x16x32_bf16 v[36:39], v[136:139], v[98:101], v[36:39]
	v_mfma_f32_16x16x32_bf16 v[32:35], v[140:143], v[98:101], v[32:35]
	v_mfma_f32_16x16x32_bf16 v[20:23], v[136:139], v[120:123], v[20:23]
	v_mfma_f32_16x16x32_bf16 v[16:19], v[140:143], v[120:123], v[16:19]
	v_mfma_f32_16x16x32_bf16 v[0:3], v[140:143], v[124:127], v[0:3]
	v_mfma_f32_16x16x32_bf16 v[86:89], v[128:131], v[98:101], v[44:47]
	v_mfma_f32_16x16x32_bf16 v[98:101], v[128:131], v[120:123], v[28:31]
	v_mfma_f32_16x16x32_bf16 v[144:147], v[132:135], v[120:123], v[24:27]
	v_mfma_f32_16x16x32_bf16 v[120:123], v[128:131], v[124:127], v[12:15]
	v_mfma_f32_16x16x32_bf16 v[128:131], v[132:135], v[124:127], v[8:11]
	v_mfma_f32_16x16x32_bf16 v[132:135], v[136:139], v[124:127], v[4:7]
	s_setprio 0
	s_nop 1
	ds_read_b128 v[4:7], v94 offset:16384
	ds_read_b128 v[8:11], v94 offset:18432
	ds_read_b128 v[124:127], v94 offset:20480
	ds_read_b128 v[136:139], v94 offset:22528
	ds_read_b128 v[140:143], v95 offset:49152
	ds_read_b128 v[148:151], v95 offset:51200
	ds_read_b128 v[152:155], v95 offset:53248
	ds_read_b128 v[156:159], v95 offset:55296
	s_setprio 1
	s_waitcnt lgkmcnt(3)
	v_mfma_f32_16x16x32_bf16 v[60:63], v[140:143], v[4:7], v[60:63]
	s_waitcnt lgkmcnt(2)
	v_mfma_f32_16x16x32_bf16 v[44:47], v[148:151], v[4:7], v[56:59]
	s_waitcnt lgkmcnt(1)
	v_mfma_f32_16x16x32_bf16 v[28:31], v[152:155], v[4:7], v[52:55]
	s_waitcnt lgkmcnt(0)
	v_mfma_f32_16x16x32_bf16 v[12:15], v[156:159], v[4:7], v[48:51]
	v_mfma_f32_16x16x32_bf16 v[56:59], v[140:143], v[8:11], v[86:89]
	v_mfma_f32_16x16x32_bf16 v[40:43], v[148:151], v[8:11], v[40:43]
	v_mfma_f32_16x16x32_bf16 v[24:27], v[152:155], v[8:11], v[36:39]
	v_mfma_f32_16x16x32_bf16 v[8:11], v[156:159], v[8:11], v[32:35]
	v_mfma_f32_16x16x32_bf16 v[52:55], v[140:143], v[124:127], v[98:101]
	v_mfma_f32_16x16x32_bf16 v[36:39], v[148:151], v[124:127], v[144:147]
	v_mfma_f32_16x16x32_bf16 v[20:23], v[152:155], v[124:127], v[20:23]
	v_mfma_f32_16x16x32_bf16 v[4:7], v[156:159], v[124:127], v[16:19]
	v_mfma_f32_16x16x32_bf16 v[48:51], v[140:143], v[136:139], v[120:123]
	v_mfma_f32_16x16x32_bf16 v[32:35], v[148:151], v[136:139], v[128:131]
	v_mfma_f32_16x16x32_bf16 v[16:19], v[152:155], v[136:139], v[132:135]
	v_mfma_f32_16x16x32_bf16 v[0:3], v[156:159], v[136:139], v[0:3]
	s_setprio 0
	s_waitcnt vmcnt(0)
	s_cmpk_gt_i32 s1, 0x7f
	s_barrier
	s_cbranch_scc0 .LBB0_885
	s_add_i32 s0, s24, 0xffffc000
	s_lshr_b32 s0, s0, 8
	v_readlane_b32 s6, v180, 24
	s_add_i32 s6, s0, s6
	s_and_b32 s10, s24, 0x80
	s_lshl_b64 s[8:9], s[6:7], 8
	v_readlane_b32 s36, v182, 19
	s_or_b32 s8, s8, s10
	s_mov_b64 s[10:11], 0
	v_readlane_b32 s37, v182, 20
	s_branch .LBB0_886

.LBB0_895:
	s_setprio 3
	s_and_b32 s0, s10, 0x2000
	s_xor_b32 s1, s0, 0x2000
	s_lshl_b32 s101, s1, 1
	s_add_u32 s101, s101, s100
	s_add_u32 m0, s101, 0x0
	s_nop 0
	global_load_lds_dwordx4 v[184:185], off
	s_add_u32 m0, s101, 0x1000
	v_lshl_add_u64 v[184:185], v[184:185], 0, vcc
	global_load_lds_dwordx4 v[186:187], off
	s_add_u32 m0, s101, 0x2000
	v_lshl_add_u64 v[186:187], v[186:187], 0, vcc
	global_load_lds_dwordx4 v[188:189], off
	s_add_u32 m0, s101, 0x3000
	v_lshl_add_u64 v[188:189], v[188:189], 0, vcc
	global_load_lds_dwordx4 v[190:191], off
	s_add_u32 m0, s101, 0x8000
	v_lshl_add_u64 v[190:191], v[190:191], 0, vcc
	global_load_lds_dwordx4 v[192:193], off
	s_add_u32 m0, s101, 0x9000
	v_lshl_add_u64 v[192:193], v[192:193], 0, vcc
	global_load_lds_dwordx4 v[194:195], off
	s_add_u32 m0, s101, 0xa000
	v_lshl_add_u64 v[194:195], v[194:195], 0, vcc
	global_load_lds_dwordx4 v[196:197], off
	s_add_u32 m0, s101, 0xb000
	v_lshl_add_u64 v[196:197], v[196:197], 0, vcc
	global_load_lds_dwordx4 v[198:199], off
	v_lshl_add_u64 v[198:199], v[198:199], 0, vcc
	s_lshl_b32 s0, s0, 1
	v_add_u32_e32 v68, s0, v120
	v_add_u32_e32 v102, s0, v121
	v_add_u32_e32 v98, v68, v133
	v_add_u32_e32 v103, v102, v133
	ds_read_b128 v[86:89], v98
	ds_read_b128 v[90:93], v98 offset:2048
	ds_read_b128 v[94:97], v98 offset:4096
	ds_read_b128 v[98:101], v98 offset:6144
	ds_read_b128 v[144:147], v103 offset:32768
	ds_read_b128 v[148:151], v103 offset:34816
	ds_read_b128 v[152:155], v103 offset:36864
	ds_read_b128 v[156:159], v103 offset:38912
	s_setprio 1
	s_waitcnt lgkmcnt(0)
	v_mfma_f32_16x16x32_bf16 v[60:63], v[86:89], v[144:147], v[60:63]
	v_mfma_f32_16x16x32_bf16 v[56:59], v[86:89], v[148:151], v[56:59]
	v_mfma_f32_16x16x32_bf16 v[52:55], v[86:89], v[152:155], v[52:55]
	v_mfma_f32_16x16x32_bf16 v[48:51], v[86:89], v[156:159], v[48:51]
	v_mfma_f32_16x16x32_bf16 v[44:47], v[90:93], v[144:147], v[44:47]
	v_mfma_f32_16x16x32_bf16 v[40:43], v[90:93], v[148:151], v[40:43]
	v_mfma_f32_16x16x32_bf16 v[36:39], v[90:93], v[152:155], v[36:39]
	v_mfma_f32_16x16x32_bf16 v[32:35], v[90:93], v[156:159], v[32:35]
	v_mfma_f32_16x16x32_bf16 v[28:31], v[94:97], v[144:147], v[28:31]
	v_mfma_f32_16x16x32_bf16 v[24:27], v[94:97], v[148:151], v[24:27]
	v_mfma_f32_16x16x32_bf16 v[20:23], v[94:97], v[152:155], v[20:23]
	v_mfma_f32_16x16x32_bf16 v[16:19], v[94:97], v[156:159], v[16:19]
	v_mfma_f32_16x16x32_bf16 v[12:15], v[98:101], v[144:147], v[12:15]
	v_mfma_f32_16x16x32_bf16 v[8:11], v[98:101], v[148:151], v[8:11]
	v_mfma_f32_16x16x32_bf16 v[4:7], v[98:101], v[152:155], v[4:7]
	v_mfma_f32_16x16x32_bf16 v[0:3], v[98:101], v[156:159], v[0:3]
	s_setprio 2
	v_add_u32_e32 v68, v68, v134
	ds_read_b128 v[86:89], v68
	ds_read_b128 v[90:93], v68 offset:2048
	ds_read_b128 v[94:97], v68 offset:4096
	ds_read_b128 v[98:101], v68 offset:6144
	v_add_u32_e32 v68, v102, v134
	ds_read_b128 v[144:147], v68 offset:32768
	ds_read_b128 v[148:151], v68 offset:34816
	ds_read_b128 v[152:155], v68 offset:36864
	ds_read_b128 v[156:159], v68 offset:38912
	s_setprio 1
	s_waitcnt lgkmcnt(0)
	v_mfma_f32_16x16x32_bf16 v[60:63], v[86:89], v[144:147], v[60:63]
	v_mfma_f32_16x16x32_bf16 v[56:59], v[86:89], v[148:151], v[56:59]
	v_mfma_f32_16x16x32_bf16 v[52:55], v[86:89], v[152:155], v[52:55]
	v_mfma_f32_16x16x32_bf16 v[48:51], v[86:89], v[156:159], v[48:51]
	v_mfma_f32_16x16x32_bf16 v[44:47], v[90:93], v[144:147], v[44:47]
	v_mfma_f32_16x16x32_bf16 v[40:43], v[90:93], v[148:151], v[40:43]
	v_mfma_f32_16x16x32_bf16 v[36:39], v[90:93], v[152:155], v[36:39]
	v_mfma_f32_16x16x32_bf16 v[32:35], v[90:93], v[156:159], v[32:35]
	v_mfma_f32_16x16x32_bf16 v[28:31], v[94:97], v[144:147], v[28:31]
	v_mfma_f32_16x16x32_bf16 v[24:27], v[94:97], v[148:151], v[24:27]
	v_mfma_f32_16x16x32_bf16 v[20:23], v[94:97], v[152:155], v[20:23]
	v_mfma_f32_16x16x32_bf16 v[16:19], v[94:97], v[156:159], v[16:19]
	v_mfma_f32_16x16x32_bf16 v[12:15], v[98:101], v[144:147], v[12:15]
	v_mfma_f32_16x16x32_bf16 v[8:11], v[98:101], v[148:151], v[8:11]
	v_mfma_f32_16x16x32_bf16 v[4:7], v[98:101], v[152:155], v[4:7]
	v_mfma_f32_16x16x32_bf16 v[0:3], v[98:101], v[156:159], v[0:3]
	s_setprio 0
	s_addk_i32 s10, 0x2000
	s_waitcnt vmcnt(0)
	s_add_u32 s36, s36, 0x80
	s_addc_u32 s37, s37, 0
	s_cmpk_lg_i32 s36, 0x780
	s_waitcnt vmcnt(0)
	s_barrier
	s_cbranch_scc1 .LBB0_895
	ds_read_b128 v[82:85], v122 offset:55296
	ds_read_b128 v[86:89], v122 offset:53248
	ds_read_b128 v[90:93], v122 offset:51200
	ds_read_b128 v[94:97], v122 offset:49152
	ds_read_b128 v[98:101], v123 offset:22528
	ds_read_b128 v[144:147], v123 offset:20480
	ds_read_b128 v[148:151], v123 offset:18432
	ds_read_b128 v[152:155], v123 offset:16384
	s_setprio 1
	s_waitcnt lgkmcnt(0)
	v_mfma_f32_16x16x32_bf16 v[60:63], v[152:155], v[94:97], v[60:63]
	v_mfma_f32_16x16x32_bf16 v[52:55], v[152:155], v[86:89], v[52:55]
	v_mfma_f32_16x16x32_bf16 v[48:51], v[152:155], v[82:85], v[48:51]
	v_mfma_f32_16x16x32_bf16 v[44:47], v[148:151], v[94:97], v[44:47]
	v_mfma_f32_16x16x32_bf16 v[40:43], v[148:151], v[90:93], v[40:43]
	v_mfma_f32_16x16x32_bf16 v[36:39], v[148:151], v[86:89], v[36:39]
	v_mfma_f32_16x16x32_bf16 v[32:35], v[148:151], v[82:85], v[32:35]
	v_mfma_f32_16x16x32_bf16 v[4:7], v[98:101], v[86:89], v[4:7]
	v_mfma_f32_16x16x32_bf16 v[156:159], v[152:155], v[90:93], v[56:59]
	v_mfma_f32_16x16x32_bf16 v[148:151], v[144:147], v[94:97], v[28:31]
	v_mfma_f32_16x16x32_bf16 v[152:155], v[144:147], v[90:93], v[24:27]
	v_mfma_f32_16x16x32_bf16 v[160:163], v[144:147], v[86:89], v[20:23]
	v_mfma_f32_16x16x32_bf16 v[144:147], v[144:147], v[82:85], v[16:19]
	v_mfma_f32_16x16x32_bf16 v[94:97], v[98:101], v[94:97], v[12:15]
	v_mfma_f32_16x16x32_bf16 v[90:93], v[98:101], v[90:93], v[8:11]
	v_mfma_f32_16x16x32_bf16 v[82:85], v[98:101], v[82:85], v[0:3]
	s_setprio 0
	s_nop 1
	ds_read_b128 v[0:3], v124 offset:16384
	ds_read_b128 v[8:11], v124 offset:18432
	ds_read_b128 v[12:15], v124 offset:20480
	ds_read_b128 v[86:89], v124 offset:22528
	ds_read_b128 v[98:101], v125 offset:49152
	ds_read_b128 v[164:167], v125 offset:51200
	ds_read_b128 v[168:171], v125 offset:53248
	ds_read_b128 v[172:175], v125 offset:55296
	s_setprio 1
	s_waitcnt lgkmcnt(3)
	v_mfma_f32_16x16x32_bf16 v[56:59], v[0:3], v[98:101], v[60:63]
	s_waitcnt lgkmcnt(2)
	v_mfma_f32_16x16x32_bf16 v[60:63], v[0:3], v[164:167], v[156:159]
	s_waitcnt lgkmcnt(1)
	v_mfma_f32_16x16x32_bf16 v[24:27], v[0:3], v[168:171], v[52:55]
	s_waitcnt lgkmcnt(0)
	v_mfma_f32_16x16x32_bf16 v[28:31], v[0:3], v[172:175], v[48:51]
	v_mfma_f32_16x16x32_bf16 v[52:55], v[8:11], v[98:101], v[44:47]
	v_mfma_f32_16x16x32_bf16 v[48:51], v[8:11], v[164:167], v[40:43]
	v_mfma_f32_16x16x32_bf16 v[16:19], v[8:11], v[168:171], v[36:39]
	v_mfma_f32_16x16x32_bf16 v[20:23], v[8:11], v[172:175], v[32:35]
	v_mfma_f32_16x16x32_bf16 v[40:43], v[12:15], v[98:101], v[148:151]
	v_mfma_f32_16x16x32_bf16 v[44:47], v[12:15], v[164:167], v[152:155]
	v_mfma_f32_16x16x32_bf16 v[8:11], v[12:15], v[168:171], v[160:163]
	v_mfma_f32_16x16x32_bf16 v[12:15], v[12:15], v[172:175], v[144:147]
	v_mfma_f32_16x16x32_bf16 v[32:35], v[86:89], v[98:101], v[94:97]
	v_mfma_f32_16x16x32_bf16 v[36:39], v[86:89], v[164:167], v[90:93]
	v_mfma_f32_16x16x32_bf16 v[0:3], v[86:89], v[168:171], v[4:7]
	v_mfma_f32_16x16x32_bf16 v[4:7], v[86:89], v[172:175], v[82:85]
	s_setprio 0
	s_waitcnt vmcnt(0)
	s_cmpk_lt_i32 s9, 0x80
	s_cselect_b64 s[42:43], -1, 0
	s_cmpk_gt_i32 s9, 0x7f
	s_mov_b64 s[0:1], -1
	s_barrier
	s_cbranch_scc0 .LBB0_904
	s_and_b32 s10, s20, 0x80
	s_cbranch_execz .LBB0_905

.LBB0_1239:
	s_setprio 3
	s_and_b32 s9, s8, 0x2000
	s_xor_b32 s18, s9, 0x2000
	s_lshl_b32 s101, s18, 1
	s_add_u32 s101, s101, s100
	s_add_u32 m0, s101, 0x0
	s_nop 0
	global_load_lds_dwordx4 v[184:185], off
	s_add_u32 m0, s101, 0x1000
	v_lshl_add_u64 v[184:185], v[184:185], 0, vcc
	global_load_lds_dwordx4 v[186:187], off
	s_add_u32 m0, s101, 0x2000
	v_lshl_add_u64 v[186:187], v[186:187], 0, vcc
	global_load_lds_dwordx4 v[188:189], off
	s_add_u32 m0, s101, 0x3000
	v_lshl_add_u64 v[188:189], v[188:189], 0, vcc
	global_load_lds_dwordx4 v[190:191], off
	s_add_u32 m0, s101, 0x8000
	v_lshl_add_u64 v[190:191], v[190:191], 0, vcc
	global_load_lds_dwordx4 v[192:193], off
	s_add_u32 m0, s101, 0x9000
	v_lshl_add_u64 v[192:193], v[192:193], 0, vcc
	global_load_lds_dwordx4 v[194:195], off
	s_add_u32 m0, s101, 0xa000
	v_lshl_add_u64 v[194:195], v[194:195], 0, vcc
	global_load_lds_dwordx4 v[196:197], off
	s_add_u32 m0, s101, 0xb000
	v_lshl_add_u64 v[196:197], v[196:197], 0, vcc
	global_load_lds_dwordx4 v[198:199], off
	v_lshl_add_u64 v[198:199], v[198:199], 0, vcc
	s_lshl_b32 s9, s9, 1
	v_add_u32_e32 v136, s9, v84
	v_add_u32_e32 v137, s9, v83
	v_add_u32_e32 v100, v136, v86
	v_add_u32_e32 v132, v137, v86
	ds_read_b128 v[88:91], v100
	ds_read_b128 v[92:95], v100 offset:2048
	ds_read_b128 v[96:99], v100 offset:4096
	ds_read_b128 v[100:103], v100 offset:6144
	ds_read_b128 v[120:123], v132 offset:32768
	ds_read_b128 v[124:127], v132 offset:34816
	ds_read_b128 v[128:131], v132 offset:36864
	ds_read_b128 v[132:135], v132 offset:38912
	s_setprio 1
	s_waitcnt lgkmcnt(0)
	v_mfma_f32_16x16x32_bf16 v[60:63], v[120:123], v[88:91], v[60:63]
	v_mfma_f32_16x16x32_bf16 v[56:59], v[124:127], v[88:91], v[56:59]
	v_mfma_f32_16x16x32_bf16 v[52:55], v[128:131], v[88:91], v[52:55]
	v_mfma_f32_16x16x32_bf16 v[48:51], v[132:135], v[88:91], v[48:51]
	v_mfma_f32_16x16x32_bf16 v[44:47], v[120:123], v[92:95], v[44:47]
	v_mfma_f32_16x16x32_bf16 v[40:43], v[124:127], v[92:95], v[40:43]
	v_mfma_f32_16x16x32_bf16 v[36:39], v[128:131], v[92:95], v[36:39]
	v_mfma_f32_16x16x32_bf16 v[32:35], v[132:135], v[92:95], v[32:35]
	v_mfma_f32_16x16x32_bf16 v[28:31], v[120:123], v[96:99], v[28:31]
	v_mfma_f32_16x16x32_bf16 v[24:27], v[124:127], v[96:99], v[24:27]
	v_mfma_f32_16x16x32_bf16 v[20:23], v[128:131], v[96:99], v[20:23]
	v_mfma_f32_16x16x32_bf16 v[16:19], v[132:135], v[96:99], v[16:19]
	v_mfma_f32_16x16x32_bf16 v[12:15], v[120:123], v[100:103], v[12:15]
	v_mfma_f32_16x16x32_bf16 v[8:11], v[124:127], v[100:103], v[8:11]
	v_mfma_f32_16x16x32_bf16 v[4:7], v[128:131], v[100:103], v[4:7]
	v_mfma_f32_16x16x32_bf16 v[0:3], v[132:135], v[100:103], v[0:3]
	s_setprio 2
	v_add_u32_e32 v100, v136, v87
	v_add_u32_e32 v132, v137, v87
	ds_read_b128 v[88:91], v100
	ds_read_b128 v[92:95], v100 offset:2048
	ds_read_b128 v[96:99], v100 offset:4096
	ds_read_b128 v[100:103], v100 offset:6144
	ds_read_b128 v[120:123], v132 offset:32768
	ds_read_b128 v[124:127], v132 offset:34816
	ds_read_b128 v[128:131], v132 offset:36864
	ds_read_b128 v[132:135], v132 offset:38912
	s_setprio 1
	s_waitcnt lgkmcnt(0)
	v_mfma_f32_16x16x32_bf16 v[60:63], v[120:123], v[88:91], v[60:63]
	v_mfma_f32_16x16x32_bf16 v[56:59], v[124:127], v[88:91], v[56:59]
	v_mfma_f32_16x16x32_bf16 v[52:55], v[128:131], v[88:91], v[52:55]
	v_mfma_f32_16x16x32_bf16 v[48:51], v[132:135], v[88:91], v[48:51]
	v_mfma_f32_16x16x32_bf16 v[44:47], v[120:123], v[92:95], v[44:47]
	v_mfma_f32_16x16x32_bf16 v[40:43], v[124:127], v[92:95], v[40:43]
	v_mfma_f32_16x16x32_bf16 v[36:39], v[128:131], v[92:95], v[36:39]
	v_mfma_f32_16x16x32_bf16 v[32:35], v[132:135], v[92:95], v[32:35]
	v_mfma_f32_16x16x32_bf16 v[28:31], v[120:123], v[96:99], v[28:31]
	v_mfma_f32_16x16x32_bf16 v[24:27], v[124:127], v[96:99], v[24:27]
	v_mfma_f32_16x16x32_bf16 v[20:23], v[128:131], v[96:99], v[20:23]
	v_mfma_f32_16x16x32_bf16 v[16:19], v[132:135], v[96:99], v[16:19]
	v_mfma_f32_16x16x32_bf16 v[12:15], v[120:123], v[100:103], v[12:15]
	v_mfma_f32_16x16x32_bf16 v[8:11], v[124:127], v[100:103], v[8:11]
	v_mfma_f32_16x16x32_bf16 v[4:7], v[128:131], v[100:103], v[4:7]
	v_mfma_f32_16x16x32_bf16 v[0:3], v[132:135], v[100:103], v[0:3]
	s_setprio 0
	s_waitcnt vmcnt(0)
	s_add_u32 s20, s20, 0x80
	s_addc_u32 s21, s21, 0
	s_addk_i32 s8, 0x2000
	s_cmp_lg_u32 s1, s20
	s_waitcnt vmcnt(0)
	s_barrier
	s_cbranch_scc1 .LBB0_1239
	s_lshl_b32 s1, s36, 14
	s_addk_i32 s1, 0x4000
	s_and_b32 s1, s1, 0x4000
	v_add_u32_e32 v132, s1, v84
	v_add_u32_e32 v133, s1, v83
	v_add_u32_e32 v96, v132, v86
	v_add_u32_e32 v128, v133, v86
	ds_read_b128 v[78:81], v96
	ds_read_b128 v[88:91], v96 offset:2048
	ds_read_b128 v[92:95], v96 offset:4096
	ds_read_b128 v[96:99], v96 offset:6144
	ds_read_b128 v[100:103], v128 offset:32768
	ds_read_b128 v[120:123], v128 offset:34816
	ds_read_b128 v[124:127], v128 offset:36864
	ds_read_b128 v[128:131], v128 offset:38912
	s_setprio 1
	s_waitcnt lgkmcnt(3)
	v_mfma_f32_16x16x32_bf16 v[60:63], v[100:103], v[78:81], v[60:63]
	s_waitcnt lgkmcnt(2)
	v_mfma_f32_16x16x32_bf16 v[56:59], v[120:123], v[78:81], v[56:59]
	s_waitcnt lgkmcnt(1)
	v_mfma_f32_16x16x32_bf16 v[52:55], v[124:127], v[78:81], v[52:55]
	s_waitcnt lgkmcnt(0)
	v_mfma_f32_16x16x32_bf16 v[48:51], v[128:131], v[78:81], v[48:51]
	v_mfma_f32_16x16x32_bf16 v[44:47], v[100:103], v[88:91], v[44:47]
	v_mfma_f32_16x16x32_bf16 v[40:43], v[120:123], v[88:91], v[40:43]
	v_mfma_f32_16x16x32_bf16 v[36:39], v[124:127], v[88:91], v[36:39]
	v_mfma_f32_16x16x32_bf16 v[32:35], v[128:131], v[88:91], v[32:35]
	v_mfma_f32_16x16x32_bf16 v[28:31], v[100:103], v[92:95], v[28:31]
	v_mfma_f32_16x16x32_bf16 v[24:27], v[120:123], v[92:95], v[24:27]
	v_mfma_f32_16x16x32_bf16 v[20:23], v[124:127], v[92:95], v[20:23]
	v_mfma_f32_16x16x32_bf16 v[16:19], v[128:131], v[92:95], v[16:19]
	v_mfma_f32_16x16x32_bf16 v[12:15], v[100:103], v[96:99], v[12:15]
	v_mfma_f32_16x16x32_bf16 v[8:11], v[120:123], v[96:99], v[8:11]
	v_mfma_f32_16x16x32_bf16 v[4:7], v[124:127], v[96:99], v[4:7]
	v_mfma_f32_16x16x32_bf16 v[0:3], v[128:131], v[96:99], v[0:3]
	s_setprio 0
	v_add_u32_e32 v96, v132, v87
	v_add_u32_e32 v128, v133, v87
	ds_read_b128 v[78:81], v96
	ds_read_b128 v[88:91], v96 offset:2048
	ds_read_b128 v[92:95], v96 offset:4096
	ds_read_b128 v[96:99], v96 offset:6144
	ds_read_b128 v[100:103], v128 offset:32768
	ds_read_b128 v[120:123], v128 offset:34816
	ds_read_b128 v[124:127], v128 offset:36864
	ds_read_b128 v[128:131], v128 offset:38912
	s_setprio 1
	s_waitcnt lgkmcnt(3)
	v_mfma_f32_16x16x32_bf16 v[60:63], v[100:103], v[78:81], v[60:63]
	s_waitcnt lgkmcnt(2)
	v_mfma_f32_16x16x32_bf16 v[56:59], v[120:123], v[78:81], v[56:59]
	s_waitcnt lgkmcnt(1)
	v_mfma_f32_16x16x32_bf16 v[52:55], v[124:127], v[78:81], v[52:55]
	s_waitcnt lgkmcnt(0)
	v_mfma_f32_16x16x32_bf16 v[48:51], v[128:131], v[78:81], v[48:51]
	v_mfma_f32_16x16x32_bf16 v[44:47], v[100:103], v[88:91], v[44:47]
	v_mfma_f32_16x16x32_bf16 v[40:43], v[120:123], v[88:91], v[40:43]
	v_mfma_f32_16x16x32_bf16 v[36:39], v[124:127], v[88:91], v[36:39]
	v_mfma_f32_16x16x32_bf16 v[32:35], v[128:131], v[88:91], v[32:35]
	v_mfma_f32_16x16x32_bf16 v[28:31], v[100:103], v[92:95], v[28:31]
	v_mfma_f32_16x16x32_bf16 v[24:27], v[120:123], v[92:95], v[24:27]
	v_mfma_f32_16x16x32_bf16 v[20:23], v[124:127], v[92:95], v[20:23]
	v_mfma_f32_16x16x32_bf16 v[16:19], v[128:131], v[92:95], v[16:19]
	v_mfma_f32_16x16x32_bf16 v[12:15], v[100:103], v[96:99], v[12:15]
	v_mfma_f32_16x16x32_bf16 v[8:11], v[120:123], v[96:99], v[8:11]
	v_mfma_f32_16x16x32_bf16 v[4:7], v[124:127], v[96:99], v[4:7]
	v_mfma_f32_16x16x32_bf16 v[0:3], v[128:131], v[96:99], v[0:3]
	s_setprio 0
	s_lshl_b32 s1, s25, 3
	s_lshl_b32 s8, s11, 1
	s_or_b32 s1, s8, s1
	s_or_b32 s1, s1, s13
	s_lshl_b32 s1, s1, 4
	s_or_b32 s8, s1, s24
	s_ashr_i32 s9, s8, 31
	s_lshl_b64 s[8:9], s[8:9], 18
	s_add_u32 s8, s52, s8
	v_add_lshl_u32 v78, s10, v71, 8
	s_addc_u32 s9, s53, s9
	v_or_b32_e32 v80, s0, v85
	v_ashrrev_i32_e32 v79, 31, v78
	v_lshl_add_u64 v[78:79], v[78:79], 1, s[8:9]
	v_cvt_pk_bf16_f32 v60, v60, v61
	v_cvt_pk_bf16_f32 v61, v62, v63
	v_lshlrev_b32_e32 v62, 1, v80
	v_mov_b32_e32 v63, v69
	v_lshl_add_u64 v[80:81], v[78:79], 0, v[62:63]
	v_cvt_pk_bf16_f32 v48, v48, v49
	v_cvt_pk_bf16_f32 v49, v50, v51
	s_mov_b64 s[0:1], 0x2000
	s_waitcnt vmcnt(0)
	s_barrier
	global_store_dwordx2 v[80:81], v[48:49], off offset:96
	v_lshl_add_u64 v[48:49], v[78:79], 0, s[0:1]
	v_cvt_pk_bf16_f32 v44, v44, v45
	v_cvt_pk_bf16_f32 v45, v46, v47
	v_lshl_add_u64 v[46:47], v[48:49], 0, v[62:63]
	v_cvt_pk_bf16_f32 v40, v40, v41
	v_cvt_pk_bf16_f32 v41, v42, v43
	v_or_b32_e32 v42, 32, v62
	v_mov_b32_e32 v43, v69
	global_store_dwordx2 v[46:47], v[44:45], off
	v_lshl_add_u64 v[44:45], v[48:49], 0, v[42:43]
	v_cvt_pk_bf16_f32 v36, v36, v37
	v_cvt_pk_bf16_f32 v37, v38, v39
	v_or_b32_e32 v38, 64, v62
	v_mov_b32_e32 v39, v69
	global_store_dwordx2 v[44:45], v[40:41], off
	v_lshl_add_u64 v[40:41], v[48:49], 0, v[38:39]
	v_cvt_pk_bf16_f32 v32, v32, v33
	v_cvt_pk_bf16_f32 v33, v34, v35
	v_or_b32_e32 v34, 0x60, v62
	v_mov_b32_e32 v35, v69
	global_store_dwordx2 v[40:41], v[36:37], off
	v_lshl_add_u64 v[36:37], v[48:49], 0, v[34:35]
	s_mov_b64 s[0:1], 0x4000
	global_store_dwordx2 v[36:37], v[32:33], off
	v_lshl_add_u64 v[32:33], v[78:79], 0, s[0:1]
	v_cvt_pk_bf16_f32 v16, v16, v17
	v_cvt_pk_bf16_f32 v17, v18, v19
	v_lshl_add_u64 v[18:19], v[32:33], 0, v[34:35]
	s_mov_b64 s[0:1], 0x6000
	global_store_dwordx2 v[18:19], v[16:17], off
	v_lshl_add_u64 v[16:17], v[78:79], 0, s[0:1]
	v_readlane_b32 s0, v181, 50
	s_add_i32 s6, s6, s84
	s_add_i32 s12, s12, s0
	v_cvt_pk_bf16_f32 v56, v56, v57
	v_cvt_pk_bf16_f32 v57, v58, v59
	v_cvt_pk_bf16_f32 v52, v52, v53
	v_cvt_pk_bf16_f32 v53, v54, v55
	v_cvt_pk_bf16_f32 v28, v28, v29
	v_cvt_pk_bf16_f32 v29, v30, v31
	v_lshl_add_u64 v[30:31], v[32:33], 0, v[62:63]
	v_cvt_pk_bf16_f32 v24, v24, v25
	v_cvt_pk_bf16_f32 v25, v26, v27
	v_lshl_add_u64 v[26:27], v[32:33], 0, v[42:43]
	v_cvt_pk_bf16_f32 v20, v20, v21
	v_cvt_pk_bf16_f32 v21, v22, v23
	v_lshl_add_u64 v[22:23], v[32:33], 0, v[38:39]
	v_cvt_pk_bf16_f32 v12, v12, v13
	v_cvt_pk_bf16_f32 v13, v14, v15
	v_lshl_add_u64 v[14:15], v[16:17], 0, v[62:63]
	v_cvt_pk_bf16_f32 v8, v8, v9
	v_cvt_pk_bf16_f32 v9, v10, v11
	v_lshl_add_u64 v[10:11], v[16:17], 0, v[42:43]
	v_cvt_pk_bf16_f32 v4, v4, v5
	v_cvt_pk_bf16_f32 v5, v6, v7
	v_lshl_add_u64 v[6:7], v[16:17], 0, v[38:39]
	v_cvt_pk_bf16_f32 v0, v0, v1
	v_cvt_pk_bf16_f32 v1, v2, v3
	v_lshl_add_u64 v[2:3], v[16:17], 0, v[34:35]
	s_cmpk_lt_i32 s6, 0x800
	global_store_dwordx2 v[80:81], v[60:61], off
	global_store_dwordx2 v[80:81], v[56:57], off offset:32
	global_store_dwordx2 v[80:81], v[52:53], off offset:64
	global_store_dwordx2 v[30:31], v[28:29], off
	global_store_dwordx2 v[26:27], v[24:25], off
	global_store_dwordx2 v[22:23], v[20:21], off
	global_store_dwordx2 v[14:15], v[12:13], off
	global_store_dwordx2 v[10:11], v[8:9], off
	global_store_dwordx2 v[6:7], v[4:5], off
	global_store_dwordx2 v[2:3], v[0:1], off
	s_cbranch_scc1 .LBB0_1234
	v_readlane_b32 s50, v180, 0
	s_mov_b32 s18, 0x42ce8ed0
	s_mov_b32 s19, 0xc2b17218
	s_mov_b32 s48, s5
	v_readlane_b32 s51, v180, 1

.LBB0_1487:
	s_setprio 3
	s_and_b32 s6, s0, 0x2000
	s_xor_b32 s8, s6, 0x2000
	s_lshl_b32 s101, s8, 1
	s_add_u32 s101, s101, s100
	s_add_u32 m0, s101, 0x0
	s_nop 0
	global_load_lds_dwordx4 v[184:185], off
	s_add_u32 m0, s101, 0x1000
	v_lshl_add_u64 v[184:185], v[184:185], 0, vcc
	global_load_lds_dwordx4 v[186:187], off
	s_add_u32 m0, s101, 0x2000
	v_lshl_add_u64 v[186:187], v[186:187], 0, vcc
	global_load_lds_dwordx4 v[188:189], off
	s_add_u32 m0, s101, 0x3000
	v_lshl_add_u64 v[188:189], v[188:189], 0, vcc
	global_load_lds_dwordx4 v[190:191], off
	s_add_u32 m0, s101, 0x8000
	v_lshl_add_u64 v[190:191], v[190:191], 0, vcc
	global_load_lds_dwordx4 v[192:193], off
	s_add_u32 m0, s101, 0x9000
	v_lshl_add_u64 v[192:193], v[192:193], 0, vcc
	global_load_lds_dwordx4 v[194:195], off
	s_add_u32 m0, s101, 0xa000
	v_lshl_add_u64 v[194:195], v[194:195], 0, vcc
	global_load_lds_dwordx4 v[196:197], off
	s_add_u32 m0, s101, 0xb000
	v_lshl_add_u64 v[196:197], v[196:197], 0, vcc
	global_load_lds_dwordx4 v[198:199], off
	v_lshl_add_u64 v[198:199], v[198:199], 0, vcc
	s_lshl_b32 s6, s6, 1
	v_add_u32_e32 v148, s6, v92
	v_add_u32_e32 v149, s6, v71
	v_add_u32_e32 v128, v148, v98
	v_add_u32_e32 v144, v149, v98
	ds_read_b128 v[100:103], v128
	ds_read_b128 v[120:123], v128 offset:2048
	ds_read_b128 v[124:127], v128 offset:4096
	ds_read_b128 v[128:131], v128 offset:6144
	ds_read_b128 v[132:135], v144 offset:32768
	ds_read_b128 v[136:139], v144 offset:34816
	ds_read_b128 v[140:143], v144 offset:36864
	ds_read_b128 v[144:147], v144 offset:38912
	s_setprio 1
	s_waitcnt lgkmcnt(0)
	v_mfma_f32_16x16x32_bf16 v[60:63], v[132:135], v[100:103], v[60:63]
	v_mfma_f32_16x16x32_bf16 v[56:59], v[136:139], v[100:103], v[56:59]
	v_mfma_f32_16x16x32_bf16 v[52:55], v[140:143], v[100:103], v[52:55]
	v_mfma_f32_16x16x32_bf16 v[48:51], v[144:147], v[100:103], v[48:51]
	v_mfma_f32_16x16x32_bf16 v[44:47], v[132:135], v[120:123], v[44:47]
	v_mfma_f32_16x16x32_bf16 v[40:43], v[136:139], v[120:123], v[40:43]
	v_mfma_f32_16x16x32_bf16 v[36:39], v[140:143], v[120:123], v[36:39]
	v_mfma_f32_16x16x32_bf16 v[32:35], v[144:147], v[120:123], v[32:35]
	v_mfma_f32_16x16x32_bf16 v[28:31], v[132:135], v[124:127], v[28:31]
	v_mfma_f32_16x16x32_bf16 v[24:27], v[136:139], v[124:127], v[24:27]
	v_mfma_f32_16x16x32_bf16 v[20:23], v[140:143], v[124:127], v[20:23]
	v_mfma_f32_16x16x32_bf16 v[16:19], v[144:147], v[124:127], v[16:19]
	v_mfma_f32_16x16x32_bf16 v[12:15], v[132:135], v[128:131], v[12:15]
	v_mfma_f32_16x16x32_bf16 v[8:11], v[136:139], v[128:131], v[8:11]
	v_mfma_f32_16x16x32_bf16 v[4:7], v[140:143], v[128:131], v[4:7]
	v_mfma_f32_16x16x32_bf16 v[0:3], v[144:147], v[128:131], v[0:3]
	s_setprio 2
	v_add_u32_e32 v128, v148, v99
	v_add_u32_e32 v144, v149, v99
	ds_read_b128 v[100:103], v128
	ds_read_b128 v[120:123], v128 offset:2048
	ds_read_b128 v[124:127], v128 offset:4096
	ds_read_b128 v[128:131], v128 offset:6144
	ds_read_b128 v[132:135], v144 offset:32768
	ds_read_b128 v[136:139], v144 offset:34816
	ds_read_b128 v[140:143], v144 offset:36864
	ds_read_b128 v[144:147], v144 offset:38912
	s_setprio 1
	s_waitcnt lgkmcnt(0)
	v_mfma_f32_16x16x32_bf16 v[60:63], v[132:135], v[100:103], v[60:63]
	v_mfma_f32_16x16x32_bf16 v[56:59], v[136:139], v[100:103], v[56:59]
	v_mfma_f32_16x16x32_bf16 v[52:55], v[140:143], v[100:103], v[52:55]
	v_mfma_f32_16x16x32_bf16 v[48:51], v[144:147], v[100:103], v[48:51]
	v_mfma_f32_16x16x32_bf16 v[44:47], v[132:135], v[120:123], v[44:47]
	v_mfma_f32_16x16x32_bf16 v[40:43], v[136:139], v[120:123], v[40:43]
	v_mfma_f32_16x16x32_bf16 v[36:39], v[140:143], v[120:123], v[36:39]
	v_mfma_f32_16x16x32_bf16 v[32:35], v[144:147], v[120:123], v[32:35]
	v_mfma_f32_16x16x32_bf16 v[28:31], v[132:135], v[124:127], v[28:31]
	v_mfma_f32_16x16x32_bf16 v[24:27], v[136:139], v[124:127], v[24:27]
	v_mfma_f32_16x16x32_bf16 v[20:23], v[140:143], v[124:127], v[20:23]
	v_mfma_f32_16x16x32_bf16 v[16:19], v[144:147], v[124:127], v[16:19]
	v_mfma_f32_16x16x32_bf16 v[12:15], v[132:135], v[128:131], v[12:15]
	v_mfma_f32_16x16x32_bf16 v[8:11], v[136:139], v[128:131], v[8:11]
	v_mfma_f32_16x16x32_bf16 v[4:7], v[140:143], v[128:131], v[4:7]
	v_mfma_f32_16x16x32_bf16 v[0:3], v[144:147], v[128:131], v[0:3]
	s_setprio 0
	s_waitcnt vmcnt(0)
	s_add_u32 s36, s36, 0x80
	s_addc_u32 s37, s37, 0
	s_addk_i32 s0, 0x2000
	s_cmpk_lg_i32 s36, 0xf80
	s_waitcnt vmcnt(0)
	s_barrier
	s_cbranch_scc1 .LBB0_1487
	ds_read_b128 v[88:91], v94 offset:16384
	ds_read_b128 v[100:103], v94 offset:18432
	ds_read_b128 v[120:123], v94 offset:20480
	ds_read_b128 v[124:127], v94 offset:22528
	ds_read_b128 v[128:131], v95 offset:49152
	ds_read_b128 v[132:135], v95 offset:51200
	ds_read_b128 v[136:139], v95 offset:53248
	ds_read_b128 v[140:143], v95 offset:55296
	s_setprio 1
	s_waitcnt lgkmcnt(3)
	v_mfma_f32_16x16x32_bf16 v[60:63], v[128:131], v[88:91], v[60:63]
	s_waitcnt lgkmcnt(2)
	v_mfma_f32_16x16x32_bf16 v[56:59], v[132:135], v[88:91], v[56:59]
	s_waitcnt lgkmcnt(1)
	v_mfma_f32_16x16x32_bf16 v[52:55], v[136:139], v[88:91], v[52:55]
	s_waitcnt lgkmcnt(0)
	v_mfma_f32_16x16x32_bf16 v[48:51], v[140:143], v[88:91], v[48:51]
	v_mfma_f32_16x16x32_bf16 v[40:43], v[132:135], v[100:103], v[40:43]
	v_mfma_f32_16x16x32_bf16 v[36:39], v[136:139], v[100:103], v[36:39]
	v_mfma_f32_16x16x32_bf16 v[32:35], v[140:143], v[100:103], v[32:35]
	v_mfma_f32_16x16x32_bf16 v[20:23], v[136:139], v[120:123], v[20:23]
	v_mfma_f32_16x16x32_bf16 v[16:19], v[140:143], v[120:123], v[16:19]
	v_mfma_f32_16x16x32_bf16 v[0:3], v[140:143], v[124:127], v[0:3]
	v_mfma_f32_16x16x32_bf16 v[88:91], v[128:131], v[100:103], v[44:47]
	v_mfma_f32_16x16x32_bf16 v[100:103], v[128:131], v[120:123], v[28:31]
	v_mfma_f32_16x16x32_bf16 v[144:147], v[132:135], v[120:123], v[24:27]
	v_mfma_f32_16x16x32_bf16 v[120:123], v[128:131], v[124:127], v[12:15]
	v_mfma_f32_16x16x32_bf16 v[128:131], v[132:135], v[124:127], v[8:11]
	v_mfma_f32_16x16x32_bf16 v[132:135], v[136:139], v[124:127], v[4:7]
	s_setprio 0
	s_nop 1
	ds_read_b128 v[4:7], v96 offset:16384
	ds_read_b128 v[8:11], v96 offset:18432
	ds_read_b128 v[124:127], v96 offset:20480
	ds_read_b128 v[136:139], v96 offset:22528
	ds_read_b128 v[140:143], v97 offset:49152
	ds_read_b128 v[148:151], v97 offset:51200
	ds_read_b128 v[152:155], v97 offset:53248
	ds_read_b128 v[156:159], v97 offset:55296
	s_setprio 1
	s_waitcnt lgkmcnt(3)
	v_mfma_f32_16x16x32_bf16 v[60:63], v[140:143], v[4:7], v[60:63]
	s_waitcnt lgkmcnt(2)
	v_mfma_f32_16x16x32_bf16 v[44:47], v[148:151], v[4:7], v[56:59]
	s_waitcnt lgkmcnt(1)
	v_mfma_f32_16x16x32_bf16 v[28:31], v[152:155], v[4:7], v[52:55]
	s_waitcnt lgkmcnt(0)
	v_mfma_f32_16x16x32_bf16 v[12:15], v[156:159], v[4:7], v[48:51]
	v_mfma_f32_16x16x32_bf16 v[56:59], v[140:143], v[8:11], v[88:91]
	v_mfma_f32_16x16x32_bf16 v[40:43], v[148:151], v[8:11], v[40:43]
	v_mfma_f32_16x16x32_bf16 v[24:27], v[152:155], v[8:11], v[36:39]
	v_mfma_f32_16x16x32_bf16 v[8:11], v[156:159], v[8:11], v[32:35]
	v_mfma_f32_16x16x32_bf16 v[52:55], v[140:143], v[124:127], v[100:103]
	v_mfma_f32_16x16x32_bf16 v[36:39], v[148:151], v[124:127], v[144:147]
	v_mfma_f32_16x16x32_bf16 v[20:23], v[152:155], v[124:127], v[20:23]
	v_mfma_f32_16x16x32_bf16 v[4:7], v[156:159], v[124:127], v[16:19]
	v_mfma_f32_16x16x32_bf16 v[48:51], v[140:143], v[136:139], v[120:123]
	v_mfma_f32_16x16x32_bf16 v[32:35], v[148:151], v[136:139], v[128:131]
	v_mfma_f32_16x16x32_bf16 v[16:19], v[152:155], v[136:139], v[132:135]
	v_mfma_f32_16x16x32_bf16 v[0:3], v[156:159], v[136:139], v[0:3]
	s_setprio 0
	s_waitcnt vmcnt(0)
	s_cmpk_gt_i32 s1, 0x7f
	s_barrier
	s_cbranch_scc0 .LBB0_1490
	s_add_i32 s0, s24, 0xffffc000
	s_lshr_b32 s0, s0, 8
	v_readlane_b32 s6, v180, 24
	s_add_i32 s6, s0, s6
	s_and_b32 s10, s24, 0x80
	s_lshl_b64 s[8:9], s[6:7], 8
	v_readlane_b32 s36, v182, 19
	s_or_b32 s8, s8, s10
	s_mov_b64 s[10:11], 0
	v_readlane_b32 s37, v182, 20
	s_branch .LBB0_1491

.LBB0_1498:
	s_setprio 3
	s_and_b32 s10, s6, 0x2000
	s_xor_b32 s8, s10, 0x2000
	s_lshl_b32 s101, s8, 1
	s_add_u32 s101, s101, s100
	s_add_u32 m0, s101, 0x0
	s_nop 0
	global_load_lds_dwordx4 v[184:185], off
	s_add_u32 m0, s101, 0x1000
	v_lshl_add_u64 v[184:185], v[184:185], 0, vcc
	global_load_lds_dwordx4 v[186:187], off
	s_add_u32 m0, s101, 0x2000
	v_lshl_add_u64 v[186:187], v[186:187], 0, vcc
	global_load_lds_dwordx4 v[188:189], off
	s_add_u32 m0, s101, 0x3000
	v_lshl_add_u64 v[188:189], v[188:189], 0, vcc
	global_load_lds_dwordx4 v[190:191], off
	s_add_u32 m0, s101, 0x8000
	v_lshl_add_u64 v[190:191], v[190:191], 0, vcc
	global_load_lds_dwordx4 v[192:193], off
	s_add_u32 m0, s101, 0x9000
	v_lshl_add_u64 v[192:193], v[192:193], 0, vcc
	global_load_lds_dwordx4 v[194:195], off
	s_add_u32 m0, s101, 0xa000
	v_lshl_add_u64 v[194:195], v[194:195], 0, vcc
	global_load_lds_dwordx4 v[196:197], off
	s_add_u32 m0, s101, 0xb000
	v_lshl_add_u64 v[196:197], v[196:197], 0, vcc
	global_load_lds_dwordx4 v[198:199], off
	v_lshl_add_u64 v[198:199], v[198:199], 0, vcc
	s_lshl_b32 s8, s10, 1
	v_add_u32_e32 v68, s8, v84
	v_add_u32_e32 v140, s8, v83
	v_add_u32_e32 v120, v68, v90
	v_add_u32_e32 v136, v140, v90
	ds_read_b128 v[92:95], v120
	ds_read_b128 v[96:99], v120 offset:2048
	ds_read_b128 v[100:103], v120 offset:4096
	ds_read_b128 v[120:123], v120 offset:6144
	ds_read_b128 v[124:127], v136 offset:32768
	ds_read_b128 v[128:131], v136 offset:34816
	ds_read_b128 v[132:135], v136 offset:36864
	ds_read_b128 v[136:139], v136 offset:38912
	s_setprio 1
	s_waitcnt lgkmcnt(0)
	v_mfma_f32_16x16x32_bf16 v[60:63], v[124:127], v[92:95], v[60:63]
	v_mfma_f32_16x16x32_bf16 v[56:59], v[128:131], v[92:95], v[56:59]
	v_mfma_f32_16x16x32_bf16 v[52:55], v[132:135], v[92:95], v[52:55]
	v_mfma_f32_16x16x32_bf16 v[48:51], v[136:139], v[92:95], v[48:51]
	v_mfma_f32_16x16x32_bf16 v[44:47], v[124:127], v[96:99], v[44:47]
	v_mfma_f32_16x16x32_bf16 v[40:43], v[128:131], v[96:99], v[40:43]
	v_mfma_f32_16x16x32_bf16 v[36:39], v[132:135], v[96:99], v[36:39]
	v_mfma_f32_16x16x32_bf16 v[32:35], v[136:139], v[96:99], v[32:35]
	v_mfma_f32_16x16x32_bf16 v[28:31], v[124:127], v[100:103], v[28:31]
	v_mfma_f32_16x16x32_bf16 v[24:27], v[128:131], v[100:103], v[24:27]
	v_mfma_f32_16x16x32_bf16 v[20:23], v[132:135], v[100:103], v[20:23]
	v_mfma_f32_16x16x32_bf16 v[16:19], v[136:139], v[100:103], v[16:19]
	v_mfma_f32_16x16x32_bf16 v[12:15], v[124:127], v[120:123], v[12:15]
	v_mfma_f32_16x16x32_bf16 v[8:11], v[128:131], v[120:123], v[8:11]
	v_mfma_f32_16x16x32_bf16 v[4:7], v[132:135], v[120:123], v[4:7]
	v_mfma_f32_16x16x32_bf16 v[0:3], v[136:139], v[120:123], v[0:3]
	s_setprio 2
	v_add_u32_e32 v68, v68, v91
	ds_read_b128 v[92:95], v68
	ds_read_b128 v[96:99], v68 offset:2048
	ds_read_b128 v[100:103], v68 offset:4096
	ds_read_b128 v[120:123], v68 offset:6144
	v_add_u32_e32 v68, v140, v91
	ds_read_b128 v[124:127], v68 offset:32768
	ds_read_b128 v[128:131], v68 offset:34816
	ds_read_b128 v[132:135], v68 offset:36864
	ds_read_b128 v[136:139], v68 offset:38912
	s_setprio 1
	s_waitcnt lgkmcnt(0)
	v_mfma_f32_16x16x32_bf16 v[60:63], v[124:127], v[92:95], v[60:63]
	v_mfma_f32_16x16x32_bf16 v[56:59], v[128:131], v[92:95], v[56:59]
	v_mfma_f32_16x16x32_bf16 v[52:55], v[132:135], v[92:95], v[52:55]
	v_mfma_f32_16x16x32_bf16 v[48:51], v[136:139], v[92:95], v[48:51]
	v_mfma_f32_16x16x32_bf16 v[44:47], v[124:127], v[96:99], v[44:47]
	v_mfma_f32_16x16x32_bf16 v[40:43], v[128:131], v[96:99], v[40:43]
	v_mfma_f32_16x16x32_bf16 v[36:39], v[132:135], v[96:99], v[36:39]
	v_mfma_f32_16x16x32_bf16 v[32:35], v[136:139], v[96:99], v[32:35]
	v_mfma_f32_16x16x32_bf16 v[28:31], v[124:127], v[100:103], v[28:31]
	v_mfma_f32_16x16x32_bf16 v[24:27], v[128:131], v[100:103], v[24:27]
	v_mfma_f32_16x16x32_bf16 v[20:23], v[132:135], v[100:103], v[20:23]
	v_mfma_f32_16x16x32_bf16 v[16:19], v[136:139], v[100:103], v[16:19]
	v_mfma_f32_16x16x32_bf16 v[12:15], v[124:127], v[120:123], v[12:15]
	v_mfma_f32_16x16x32_bf16 v[8:11], v[128:131], v[120:123], v[8:11]
	v_mfma_f32_16x16x32_bf16 v[4:7], v[132:135], v[120:123], v[4:7]
	v_mfma_f32_16x16x32_bf16 v[0:3], v[136:139], v[120:123], v[0:3]
	s_setprio 0
	s_addk_i32 s6, 0x2000
	s_waitcnt vmcnt(0)
	s_add_u32 s36, s36, 0x80
	s_addc_u32 s37, s37, 0
	s_cmpk_lg_i32 s36, 0x780
	s_waitcnt vmcnt(0)
	s_barrier
	s_cbranch_scc1 .LBB0_1498
	ds_read_b128 v[78:81], v85 offset:55296
	ds_read_b128 v[92:95], v85 offset:53248
	ds_read_b128 v[96:99], v85 offset:51200
	ds_read_b128 v[100:103], v85 offset:49152
	ds_read_b128 v[120:123], v86 offset:22528
	ds_read_b128 v[124:127], v86 offset:20480
	ds_read_b128 v[128:131], v86 offset:18432
	ds_read_b128 v[132:135], v86 offset:16384
	s_setprio 1
	s_waitcnt lgkmcnt(0)
	v_mfma_f32_16x16x32_bf16 v[60:63], v[100:103], v[132:135], v[60:63]
	v_mfma_f32_16x16x32_bf16 v[56:59], v[96:99], v[132:135], v[56:59]
	v_mfma_f32_16x16x32_bf16 v[52:55], v[92:95], v[132:135], v[52:55]
	v_mfma_f32_16x16x32_bf16 v[48:51], v[78:81], v[132:135], v[48:51]
	v_mfma_f32_16x16x32_bf16 v[44:47], v[100:103], v[128:131], v[44:47]
	v_mfma_f32_16x16x32_bf16 v[40:43], v[96:99], v[128:131], v[40:43]
	v_mfma_f32_16x16x32_bf16 v[36:39], v[92:95], v[128:131], v[36:39]
	v_mfma_f32_16x16x32_bf16 v[32:35], v[78:81], v[128:131], v[32:35]
	v_mfma_f32_16x16x32_bf16 v[28:31], v[100:103], v[124:127], v[28:31]
	v_mfma_f32_16x16x32_bf16 v[24:27], v[96:99], v[124:127], v[24:27]
	v_mfma_f32_16x16x32_bf16 v[20:23], v[92:95], v[124:127], v[20:23]
	v_mfma_f32_16x16x32_bf16 v[16:19], v[78:81], v[124:127], v[16:19]
	v_mfma_f32_16x16x32_bf16 v[12:15], v[100:103], v[120:123], v[12:15]
	v_mfma_f32_16x16x32_bf16 v[8:11], v[96:99], v[120:123], v[8:11]
	v_mfma_f32_16x16x32_bf16 v[4:7], v[92:95], v[120:123], v[4:7]
	v_mfma_f32_16x16x32_bf16 v[0:3], v[78:81], v[120:123], v[0:3]
	s_setprio 0
	ds_read_b128 v[78:81], v87 offset:16384
	ds_read_b128 v[92:95], v87 offset:18432
	ds_read_b128 v[96:99], v87 offset:20480
	ds_read_b128 v[100:103], v87 offset:22528
	ds_read_b128 v[120:123], v88 offset:49152
	ds_read_b128 v[124:127], v88 offset:51200
	ds_read_b128 v[128:131], v88 offset:53248
	ds_read_b128 v[132:135], v88 offset:55296
	s_setprio 1
	s_waitcnt lgkmcnt(3)
	v_mfma_f32_16x16x32_bf16 v[60:63], v[120:123], v[78:81], v[60:63]
	s_waitcnt lgkmcnt(2)
	v_mfma_f32_16x16x32_bf16 v[56:59], v[124:127], v[78:81], v[56:59]
	s_waitcnt lgkmcnt(1)
	v_mfma_f32_16x16x32_bf16 v[52:55], v[128:131], v[78:81], v[52:55]
	s_waitcnt lgkmcnt(0)
	v_mfma_f32_16x16x32_bf16 v[48:51], v[132:135], v[78:81], v[48:51]
	v_mfma_f32_16x16x32_bf16 v[44:47], v[120:123], v[92:95], v[44:47]
	v_mfma_f32_16x16x32_bf16 v[40:43], v[124:127], v[92:95], v[40:43]
	v_mfma_f32_16x16x32_bf16 v[36:39], v[128:131], v[92:95], v[36:39]
	v_mfma_f32_16x16x32_bf16 v[32:35], v[132:135], v[92:95], v[32:35]
	v_mfma_f32_16x16x32_bf16 v[28:31], v[120:123], v[96:99], v[28:31]
	v_mfma_f32_16x16x32_bf16 v[24:27], v[124:127], v[96:99], v[24:27]
	v_mfma_f32_16x16x32_bf16 v[20:23], v[128:131], v[96:99], v[20:23]
	v_mfma_f32_16x16x32_bf16 v[16:19], v[132:135], v[96:99], v[16:19]
	v_mfma_f32_16x16x32_bf16 v[12:15], v[120:123], v[100:103], v[12:15]
	v_mfma_f32_16x16x32_bf16 v[8:11], v[124:127], v[100:103], v[8:11]
	v_mfma_f32_16x16x32_bf16 v[4:7], v[128:131], v[100:103], v[4:7]
	v_mfma_f32_16x16x32_bf16 v[0:3], v[132:135], v[100:103], v[0:3]
	s_setprio 0
	s_ashr_i32 s1, s1, 4
	s_mul_hi_i32 s6, s1, 0x4200000
	s_mul_i32 s1, s1, 0x4200000
	s_add_u32 s8, s90, s1
	v_add_u32_e32 v78, s20, v71
	s_addc_u32 s9, s91, s6
	s_and_b32 s1, s24, 0x780
	v_ashrrev_i32_e32 v79, 31, v78
	v_or_b32_e32 v68, s1, v89
	v_lshlrev_b64 v[80:81], 12, v[78:79]
	v_lshl_add_u64 v[80:81], s[8:9], 0, v[80:81]
	v_lshlrev_b32_e32 v68, 1, v68
	v_cvt_pk_bf16_f32 v60, v60, v61
	v_cvt_pk_bf16_f32 v61, v62, v63
	v_lshl_add_u64 v[62:63], v[80:81], 0, v[68:69]
	v_cvt_pk_bf16_f32 v48, v48, v49
	v_cvt_pk_bf16_f32 v49, v50, v51
	s_waitcnt vmcnt(0)
	s_barrier
	global_store_dwordx2 v[62:63], v[48:49], off offset:96
	v_or_b32_e32 v48, 16, v78
	v_ashrrev_i32_e32 v49, 31, v48
	v_lshlrev_b64 v[48:49], 12, v[48:49]
	v_lshl_add_u64 v[48:49], s[8:9], 0, v[48:49]
	v_cvt_pk_bf16_f32 v44, v44, v45
	v_cvt_pk_bf16_f32 v45, v46, v47
	v_lshl_add_u64 v[46:47], v[48:49], 0, v[68:69]
	v_cvt_pk_bf16_f32 v32, v32, v33
	v_cvt_pk_bf16_f32 v33, v34, v35
	global_store_dwordx2 v[46:47], v[32:33], off offset:96
	v_or_b32_e32 v32, 32, v78
	v_ashrrev_i32_e32 v33, 31, v32
	v_lshlrev_b64 v[32:33], 12, v[32:33]
	v_lshl_add_u64 v[32:33], s[8:9], 0, v[32:33]
	v_cvt_pk_bf16_f32 v28, v28, v29
	v_cvt_pk_bf16_f32 v29, v30, v31
	v_lshl_add_u64 v[30:31], v[32:33], 0, v[68:69]
	v_cvt_pk_bf16_f32 v16, v16, v17
	v_cvt_pk_bf16_f32 v17, v18, v19
	global_store_dwordx2 v[30:31], v[16:17], off offset:96
	v_or_b32_e32 v16, 48, v78
	v_ashrrev_i32_e32 v17, 31, v16
	v_lshlrev_b64 v[16:17], 12, v[16:17]
	v_lshl_add_u64 v[16:17], s[8:9], 0, v[16:17]
	s_add_i32 s0, s0, s84
	v_cvt_pk_bf16_f32 v56, v56, v57
	v_cvt_pk_bf16_f32 v57, v58, v59
	v_cvt_pk_bf16_f32 v52, v52, v53
	v_cvt_pk_bf16_f32 v53, v54, v55
	v_cvt_pk_bf16_f32 v40, v40, v41
	v_cvt_pk_bf16_f32 v41, v42, v43
	v_cvt_pk_bf16_f32 v36, v36, v37
	v_cvt_pk_bf16_f32 v37, v38, v39
	v_cvt_pk_bf16_f32 v24, v24, v25
	v_cvt_pk_bf16_f32 v25, v26, v27
	v_cvt_pk_bf16_f32 v20, v20, v21
	v_cvt_pk_bf16_f32 v21, v22, v23
	v_cvt_pk_bf16_f32 v12, v12, v13
	v_cvt_pk_bf16_f32 v13, v14, v15
	v_lshl_add_u64 v[14:15], v[16:17], 0, v[68:69]
	v_cvt_pk_bf16_f32 v8, v8, v9
	v_cvt_pk_bf16_f32 v9, v10, v11
	v_cvt_pk_bf16_f32 v4, v4, v5
	v_cvt_pk_bf16_f32 v5, v6, v7
	v_cvt_pk_bf16_f32 v0, v0, v1
	v_cvt_pk_bf16_f32 v1, v2, v3
	s_cmpk_lt_i32 s0, 0x18c0
	global_store_dwordx2 v[62:63], v[60:61], off
	global_store_dwordx2 v[62:63], v[56:57], off offset:32
	global_store_dwordx2 v[62:63], v[52:53], off offset:64
	global_store_dwordx2 v[46:47], v[44:45], off
	global_store_dwordx2 v[46:47], v[40:41], off offset:32
	global_store_dwordx2 v[46:47], v[36:37], off offset:64
	global_store_dwordx2 v[30:31], v[28:29], off
	global_store_dwordx2 v[30:31], v[24:25], off offset:32
	global_store_dwordx2 v[30:31], v[20:21], off offset:64
	global_store_dwordx2 v[14:15], v[12:13], off
	global_store_dwordx2 v[14:15], v[8:9], off offset:32
	global_store_dwordx2 v[14:15], v[4:5], off offset:64
	global_store_dwordx2 v[14:15], v[0:1], off offset:96
	s_cbranch_scc1 .LBB0_1497

.LBB0_1707:
	s_setprio 3
	s_and_b32 s6, s0, 0x2000
	s_xor_b32 s8, s6, 0x2000
	s_lshl_b32 s101, s8, 1
	s_add_u32 s101, s101, s100
	s_add_u32 m0, s101, 0x0
	s_nop 0
	global_load_lds_dwordx4 v[184:185], off
	s_add_u32 m0, s101, 0x1000
	v_lshl_add_u64 v[184:185], v[184:185], 0, vcc
	global_load_lds_dwordx4 v[186:187], off
	s_add_u32 m0, s101, 0x2000
	v_lshl_add_u64 v[186:187], v[186:187], 0, vcc
	global_load_lds_dwordx4 v[188:189], off
	s_add_u32 m0, s101, 0x3000
	v_lshl_add_u64 v[188:189], v[188:189], 0, vcc
	global_load_lds_dwordx4 v[190:191], off
	s_add_u32 m0, s101, 0x8000
	v_lshl_add_u64 v[190:191], v[190:191], 0, vcc
	global_load_lds_dwordx4 v[192:193], off
	s_add_u32 m0, s101, 0x9000
	v_lshl_add_u64 v[192:193], v[192:193], 0, vcc
	global_load_lds_dwordx4 v[194:195], off
	s_add_u32 m0, s101, 0xa000
	v_lshl_add_u64 v[194:195], v[194:195], 0, vcc
	global_load_lds_dwordx4 v[196:197], off
	s_add_u32 m0, s101, 0xb000
	v_lshl_add_u64 v[196:197], v[196:197], 0, vcc
	global_load_lds_dwordx4 v[198:199], off
	v_lshl_add_u64 v[198:199], v[198:199], 0, vcc
	s_lshl_b32 s6, s6, 1
	v_add_u32_e32 v102, s6, v90
	v_add_u32_e32 v103, s6, v71
	v_add_u32_e32 v128, v102, v96
	v_add_u32_e32 v144, v103, v96
	ds_read_b128 v[98:101], v128
	ds_read_b128 v[120:123], v128 offset:2048
	ds_read_b128 v[124:127], v128 offset:4096
	ds_read_b128 v[128:131], v128 offset:6144
	ds_read_b128 v[132:135], v144 offset:32768
	ds_read_b128 v[136:139], v144 offset:34816
	ds_read_b128 v[140:143], v144 offset:36864
	ds_read_b128 v[144:147], v144 offset:38912
	s_setprio 1
	s_waitcnt lgkmcnt(0)
	v_mfma_f32_16x16x32_bf16 v[60:63], v[132:135], v[98:101], v[60:63]
	v_mfma_f32_16x16x32_bf16 v[56:59], v[136:139], v[98:101], v[56:59]
	v_mfma_f32_16x16x32_bf16 v[52:55], v[140:143], v[98:101], v[52:55]
	v_mfma_f32_16x16x32_bf16 v[48:51], v[144:147], v[98:101], v[48:51]
	v_mfma_f32_16x16x32_bf16 v[44:47], v[132:135], v[120:123], v[44:47]
	v_mfma_f32_16x16x32_bf16 v[40:43], v[136:139], v[120:123], v[40:43]
	v_mfma_f32_16x16x32_bf16 v[36:39], v[140:143], v[120:123], v[36:39]
	v_mfma_f32_16x16x32_bf16 v[32:35], v[144:147], v[120:123], v[32:35]
	v_mfma_f32_16x16x32_bf16 v[28:31], v[132:135], v[124:127], v[28:31]
	v_mfma_f32_16x16x32_bf16 v[24:27], v[136:139], v[124:127], v[24:27]
	v_mfma_f32_16x16x32_bf16 v[20:23], v[140:143], v[124:127], v[20:23]
	v_mfma_f32_16x16x32_bf16 v[16:19], v[144:147], v[124:127], v[16:19]
	v_mfma_f32_16x16x32_bf16 v[12:15], v[132:135], v[128:131], v[12:15]
	v_mfma_f32_16x16x32_bf16 v[8:11], v[136:139], v[128:131], v[8:11]
	v_mfma_f32_16x16x32_bf16 v[4:7], v[140:143], v[128:131], v[4:7]
	v_mfma_f32_16x16x32_bf16 v[0:3], v[144:147], v[128:131], v[0:3]
	s_setprio 2
	v_add_u32_e32 v102, v102, v97
	ds_read_b128 v[98:101], v102
	ds_read_b128 v[120:123], v102 offset:2048
	ds_read_b128 v[124:127], v102 offset:4096
	ds_read_b128 v[128:131], v102 offset:6144
	v_add_u32_e32 v102, v103, v97
	ds_read_b128 v[132:135], v102 offset:32768
	ds_read_b128 v[136:139], v102 offset:34816
	ds_read_b128 v[140:143], v102 offset:36864
	ds_read_b128 v[144:147], v102 offset:38912
	s_setprio 1
	s_waitcnt lgkmcnt(0)
	v_mfma_f32_16x16x32_bf16 v[60:63], v[132:135], v[98:101], v[60:63]
	v_mfma_f32_16x16x32_bf16 v[56:59], v[136:139], v[98:101], v[56:59]
	v_mfma_f32_16x16x32_bf16 v[52:55], v[140:143], v[98:101], v[52:55]
	v_mfma_f32_16x16x32_bf16 v[48:51], v[144:147], v[98:101], v[48:51]
	v_mfma_f32_16x16x32_bf16 v[44:47], v[132:135], v[120:123], v[44:47]
	v_mfma_f32_16x16x32_bf16 v[40:43], v[136:139], v[120:123], v[40:43]
	v_mfma_f32_16x16x32_bf16 v[36:39], v[140:143], v[120:123], v[36:39]
	v_mfma_f32_16x16x32_bf16 v[32:35], v[144:147], v[120:123], v[32:35]
	v_mfma_f32_16x16x32_bf16 v[28:31], v[132:135], v[124:127], v[28:31]
	v_mfma_f32_16x16x32_bf16 v[24:27], v[136:139], v[124:127], v[24:27]
	v_mfma_f32_16x16x32_bf16 v[20:23], v[140:143], v[124:127], v[20:23]
	v_mfma_f32_16x16x32_bf16 v[16:19], v[144:147], v[124:127], v[16:19]
	v_mfma_f32_16x16x32_bf16 v[12:15], v[132:135], v[128:131], v[12:15]
	v_mfma_f32_16x16x32_bf16 v[8:11], v[136:139], v[128:131], v[8:11]
	v_mfma_f32_16x16x32_bf16 v[4:7], v[140:143], v[128:131], v[4:7]
	v_mfma_f32_16x16x32_bf16 v[0:3], v[144:147], v[128:131], v[0:3]
	s_setprio 0
	s_waitcnt vmcnt(0)
	s_add_u32 s36, s36, 0x80
	s_addc_u32 s37, s37, 0
	s_addk_i32 s0, 0x2000
	s_cmpk_lg_i32 s36, 0xf80
	s_waitcnt vmcnt(0)
	s_barrier
	s_cbranch_scc1 .LBB0_1707
	ds_read_b128 v[86:89], v92 offset:16384
	ds_read_b128 v[98:101], v92 offset:18432
	ds_read_b128 v[120:123], v92 offset:20480
	ds_read_b128 v[124:127], v92 offset:22528
	ds_read_b128 v[128:131], v93 offset:49152
	ds_read_b128 v[132:135], v93 offset:51200
	ds_read_b128 v[136:139], v93 offset:53248
	ds_read_b128 v[140:143], v93 offset:55296
	s_setprio 1
	s_waitcnt lgkmcnt(3)
	v_mfma_f32_16x16x32_bf16 v[60:63], v[128:131], v[86:89], v[60:63]
	s_waitcnt lgkmcnt(2)
	v_mfma_f32_16x16x32_bf16 v[56:59], v[132:135], v[86:89], v[56:59]
	s_waitcnt lgkmcnt(1)
	v_mfma_f32_16x16x32_bf16 v[52:55], v[136:139], v[86:89], v[52:55]
	s_waitcnt lgkmcnt(0)
	v_mfma_f32_16x16x32_bf16 v[48:51], v[140:143], v[86:89], v[48:51]
	v_mfma_f32_16x16x32_bf16 v[40:43], v[132:135], v[98:101], v[40:43]
	v_mfma_f32_16x16x32_bf16 v[36:39], v[136:139], v[98:101], v[36:39]
	v_mfma_f32_16x16x32_bf16 v[32:35], v[140:143], v[98:101], v[32:35]
	v_mfma_f32_16x16x32_bf16 v[20:23], v[136:139], v[120:123], v[20:23]
	v_mfma_f32_16x16x32_bf16 v[16:19], v[140:143], v[120:123], v[16:19]
	v_mfma_f32_16x16x32_bf16 v[0:3], v[140:143], v[124:127], v[0:3]
	v_mfma_f32_16x16x32_bf16 v[86:89], v[128:131], v[98:101], v[44:47]
	v_mfma_f32_16x16x32_bf16 v[98:101], v[128:131], v[120:123], v[28:31]
	v_mfma_f32_16x16x32_bf16 v[144:147], v[132:135], v[120:123], v[24:27]
	v_mfma_f32_16x16x32_bf16 v[120:123], v[128:131], v[124:127], v[12:15]
	v_mfma_f32_16x16x32_bf16 v[128:131], v[132:135], v[124:127], v[8:11]
	v_mfma_f32_16x16x32_bf16 v[132:135], v[136:139], v[124:127], v[4:7]
	s_setprio 0
	s_nop 1
	ds_read_b128 v[4:7], v94 offset:16384
	ds_read_b128 v[8:11], v94 offset:18432
	ds_read_b128 v[124:127], v94 offset:20480
	ds_read_b128 v[136:139], v94 offset:22528
	ds_read_b128 v[140:143], v95 offset:49152
	ds_read_b128 v[148:151], v95 offset:51200
	ds_read_b128 v[152:155], v95 offset:53248
	ds_read_b128 v[156:159], v95 offset:55296
	s_setprio 1
	s_waitcnt lgkmcnt(3)
	v_mfma_f32_16x16x32_bf16 v[60:63], v[140:143], v[4:7], v[60:63]
	s_waitcnt lgkmcnt(2)
	v_mfma_f32_16x16x32_bf16 v[44:47], v[148:151], v[4:7], v[56:59]
	s_waitcnt lgkmcnt(1)
	v_mfma_f32_16x16x32_bf16 v[28:31], v[152:155], v[4:7], v[52:55]
	s_waitcnt lgkmcnt(0)
	v_mfma_f32_16x16x32_bf16 v[12:15], v[156:159], v[4:7], v[48:51]
	v_mfma_f32_16x16x32_bf16 v[56:59], v[140:143], v[8:11], v[86:89]
	v_mfma_f32_16x16x32_bf16 v[40:43], v[148:151], v[8:11], v[40:43]
	v_mfma_f32_16x16x32_bf16 v[24:27], v[152:155], v[8:11], v[36:39]
	v_mfma_f32_16x16x32_bf16 v[8:11], v[156:159], v[8:11], v[32:35]
	v_mfma_f32_16x16x32_bf16 v[52:55], v[140:143], v[124:127], v[98:101]
	v_mfma_f32_16x16x32_bf16 v[36:39], v[148:151], v[124:127], v[144:147]
	v_mfma_f32_16x16x32_bf16 v[20:23], v[152:155], v[124:127], v[20:23]
	v_mfma_f32_16x16x32_bf16 v[4:7], v[156:159], v[124:127], v[16:19]
	v_mfma_f32_16x16x32_bf16 v[48:51], v[140:143], v[136:139], v[120:123]
	v_mfma_f32_16x16x32_bf16 v[32:35], v[148:151], v[136:139], v[128:131]
	v_mfma_f32_16x16x32_bf16 v[16:19], v[152:155], v[136:139], v[132:135]
	v_mfma_f32_16x16x32_bf16 v[0:3], v[156:159], v[136:139], v[0:3]
	s_setprio 0
	s_waitcnt vmcnt(0)
	s_cmpk_gt_i32 s1, 0x7f
	s_barrier
	s_cbranch_scc0 .LBB0_1710
	s_add_i32 s0, s24, 0xffffc000
	s_lshr_b32 s0, s0, 8
	v_readlane_b32 s6, v180, 24
	s_add_i32 s6, s0, s6
	s_and_b32 s10, s24, 0x80
	s_lshl_b64 s[8:9], s[6:7], 8
	v_readlane_b32 s36, v182, 19
	s_or_b32 s8, s8, s10
	s_mov_b64 s[10:11], 0
	v_readlane_b32 s37, v182, 20
	s_branch .LBB0_1711
